# Q/K tile epilogue hand-written with 16B stores + start stagger (0..4.9us by bid) in multi-round GEMM phases to spread epilogue store bursts
# speedup vs baseline: 1.1110x; 1.0141x over previous
.LBB0_96:
	s_lshl_b32 s2, 1, s55
	s_and_b32 s2, s2, 0x4444
	s_cbranch_scc0 .Lstg_skip
	s_lshr_b32 s2, s54, 3
	s_and_b32 s2, s2, 7
.Lstg_loop:
	s_cmp_eq_u32 s2, 0
	s_cbranch_scc1 .Lstg_skip
	s_sleep 23
	s_sub_u32 s2, s2, 1
	s_branch .Lstg_loop

.LBB0_156:
	s_cmp_lt_u32 s20, 8
	s_cbranch_scc1 .Lqk_epi
	s_lshl_b32 s3, s20, 8
	s_and_b32 s3, s3, 0x300
	s_or_b32 s21, s3, s83
	s_cmp_gt_i32 s2, 31
	s_cselect_b64 s[22:23], -1, 0
	s_sub_i32 s3, s2, 32
	s_lshl_b32 s26, s2, 8
	s_lshr_b32 s3, s3, 2
	s_and_b32 s26, s26, 0x300
	s_cmp_lt_i32 s2, 32
	s_cselect_b64 s[56:57], -1, 0
	s_and_b64 s[34:35], s[56:57], exec
	s_cselect_b32 s33, s2, s3
	s_movk_i32 s3, 0x400
	s_cselect_b32 s35, 0x100, s3
	s_cselect_b32 s3, 0, s26
	v_add_u32_e32 v140, s3, v132
	s_ashr_i32 s3, s2, 31
	s_cmp_gt_u32 s20, 3
	s_cselect_b64 s[36:37], -1, 0
	s_and_b32 s20, s20, -4
	s_cmp_lg_u32 s20, 4
	s_cselect_b64 s[40:41], -1, 0
	s_lshl_b32 s34, s2, 4
	s_lshl_b32 s33, s33, 4
	s_lshl_b64 s[2:3], s[2:3], 19
	s_lshr_b32 s20, s21, 6
	v_lshl_add_u64 v[146:147], s[2:3], 0, v[134:135]
	s_or_b32 s2, s20, s34
	s_or_b32 s20, s33, s20
	v_or_b32_e32 v152, s21, v151
	v_ashrrev_i32_e32 v141, 31, v140
	s_ashr_i32 s3, s2, 31
	s_ashr_i32 s21, s20, 31
	s_lshl_b32 s26, s35, 1
	v_lshlrev_b64 v[144:145], 8, v[140:141]
	s_lshl_b64 s[2:3], s[2:3], 16
	s_lshl_b64 s[20:21], s[20:21], 6
	s_mov_b64 s[42:43], -1
	s_and_b64 vcc, exec, s[36:37]
	s_cbranch_vccz .LBB0_168
	s_and_b64 vcc, exec, s[40:41]
	s_cbranch_vccz .LBB0_164
	v_and_b32_e32 v178, 44, v152
	s_andn2_b64 vcc, exec, s[22:23]
	s_cbranch_vccnz .LBB0_160
	s_mov_b64 s[42:43], 0

.Lqk_epi:
	v_and_b32_e32 v140, 63, v214
	v_readfirstlane_b32 s3, v214
	v_lshrrev_b32_e32 v141, 4, v140
	v_and_b32_e32 v140, 15, v140
	s_lshr_b32 s3, s3, 6
	s_lshr_b32 s21, s3, 2
	s_and_b32 s3, s3, 3
	s_lshl_b32 s26, s2, 8
	s_lshl_b32 s33, s21, 6
	s_add_u32 s26, s26, s33
	v_add_u32_e32 v142, s26, v140
	v_lshlrev_b32_e32 v142, 10, v142
	s_and_b32 s34, s20, 3
	s_lshl_b32 s35, s34, 8
	s_lshl_b32 s40, s3, 5
	s_add_u32 s35, s35, s40
	v_and_b32_e32 v152, 1, v141
	v_lshlrev_b32_e32 v152, 4, v152
	v_lshrrev_b32_e32 v153, 1, v141
	v_lshlrev_b32_e32 v153, 3, v153
	v_add3_u32 v142, v142, v152, v153
	v_add_u32_e32 v142, s35, v142
	v_lshlrev_b32_e32 v142, 1, v142
	v_mov_b32_e32 v143, 0
	s_mov_b64 s[58:59], 0x8000
	s_mov_b64 s[60:61], 0x28000
	s_cmp_lt_u32 s20, 4
	s_cbranch_scc0 .Lqk_k
	s_add_u32 s40, s78, 0x9000000
	s_addc_u32 s41, s79, 0
	v_mov_b32_e32 v144, 0x3e38aa3b
	v_mov_b32_e32 v145, 0x3e38aa3b
	v_lshl_add_u64 v[142:143], s[40:41], 0, v[142:143]
	v_pk_mul_f32 v[124:125], v[124:125], v[144:145]
	v_pk_mul_f32 v[126:127], v[126:127], v[144:145]
	v_pk_mul_f32 v[120:121], v[120:121], v[144:145]
	v_pk_mul_f32 v[122:123], v[122:123], v[144:145]
	v_cvt_pk_bf16_f32 v124, v124, v125
	v_cvt_pk_bf16_f32 v125, v126, v127
	v_cvt_pk_bf16_f32 v126, v120, v121
	v_cvt_pk_bf16_f32 v127, v122, v123
	s_nop 1
	v_permlane16_swap_b32 v124, v126
	v_permlane16_swap_b32 v125, v127
	global_store_dwordx4 v[142:143], v[124:127], off
	v_pk_mul_f32 v[116:117], v[116:117], v[144:145]
	v_pk_mul_f32 v[118:119], v[118:119], v[144:145]
	v_pk_mul_f32 v[112:113], v[112:113], v[144:145]
	v_pk_mul_f32 v[114:115], v[114:115], v[144:145]
	v_cvt_pk_bf16_f32 v116, v116, v117
	v_cvt_pk_bf16_f32 v117, v118, v119
	v_cvt_pk_bf16_f32 v118, v112, v113
	v_cvt_pk_bf16_f32 v119, v114, v115
	s_nop 1
	v_permlane16_swap_b32 v116, v118
	v_permlane16_swap_b32 v117, v119
	global_store_dwordx4 v[142:143], v[116:119], off offset:256
	v_lshl_add_u64 v[142:143], v[142:143], 0, s[58:59]
	v_pk_mul_f32 v[108:109], v[108:109], v[144:145]
	v_pk_mul_f32 v[110:111], v[110:111], v[144:145]
	v_pk_mul_f32 v[104:105], v[104:105], v[144:145]
	v_pk_mul_f32 v[106:107], v[106:107], v[144:145]
	v_cvt_pk_bf16_f32 v108, v108, v109
	v_cvt_pk_bf16_f32 v109, v110, v111
	v_cvt_pk_bf16_f32 v110, v104, v105
	v_cvt_pk_bf16_f32 v111, v106, v107
	s_nop 1
	v_permlane16_swap_b32 v108, v110
	v_permlane16_swap_b32 v109, v111
	global_store_dwordx4 v[142:143], v[108:111], off
	v_pk_mul_f32 v[100:101], v[100:101], v[144:145]
	v_pk_mul_f32 v[102:103], v[102:103], v[144:145]
	v_pk_mul_f32 v[96:97], v[96:97], v[144:145]
	v_pk_mul_f32 v[98:99], v[98:99], v[144:145]
	v_cvt_pk_bf16_f32 v100, v100, v101
	v_cvt_pk_bf16_f32 v101, v102, v103
	v_cvt_pk_bf16_f32 v102, v96, v97
	v_cvt_pk_bf16_f32 v103, v98, v99
	s_nop 1
	v_permlane16_swap_b32 v100, v102
	v_permlane16_swap_b32 v101, v103
	global_store_dwordx4 v[142:143], v[100:103], off offset:256
	v_lshl_add_u64 v[142:143], v[142:143], 0, s[58:59]
	v_pk_mul_f32 v[92:93], v[92:93], v[144:145]
	v_pk_mul_f32 v[94:95], v[94:95], v[144:145]
	v_pk_mul_f32 v[88:89], v[88:89], v[144:145]
	v_pk_mul_f32 v[90:91], v[90:91], v[144:145]
	v_cvt_pk_bf16_f32 v92, v92, v93
	v_cvt_pk_bf16_f32 v93, v94, v95
	v_cvt_pk_bf16_f32 v94, v88, v89
	v_cvt_pk_bf16_f32 v95, v90, v91
	s_nop 1
	v_permlane16_swap_b32 v92, v94
	v_permlane16_swap_b32 v93, v95
	global_store_dwordx4 v[142:143], v[92:95], off
	v_pk_mul_f32 v[84:85], v[84:85], v[144:145]
	v_pk_mul_f32 v[86:87], v[86:87], v[144:145]
	v_pk_mul_f32 v[80:81], v[80:81], v[144:145]
	v_pk_mul_f32 v[82:83], v[82:83], v[144:145]
	v_cvt_pk_bf16_f32 v84, v84, v85
	v_cvt_pk_bf16_f32 v85, v86, v87
	v_cvt_pk_bf16_f32 v86, v80, v81
	v_cvt_pk_bf16_f32 v87, v82, v83
	s_nop 1
	v_permlane16_swap_b32 v84, v86
	v_permlane16_swap_b32 v85, v87
	global_store_dwordx4 v[142:143], v[84:87], off offset:256
	v_lshl_add_u64 v[142:143], v[142:143], 0, s[58:59]
	v_pk_mul_f32 v[76:77], v[76:77], v[144:145]
	v_pk_mul_f32 v[78:79], v[78:79], v[144:145]
	v_pk_mul_f32 v[72:73], v[72:73], v[144:145]
	v_pk_mul_f32 v[74:75], v[74:75], v[144:145]
	v_cvt_pk_bf16_f32 v76, v76, v77
	v_cvt_pk_bf16_f32 v77, v78, v79
	v_cvt_pk_bf16_f32 v78, v72, v73
	v_cvt_pk_bf16_f32 v79, v74, v75
	s_nop 1
	v_permlane16_swap_b32 v76, v78
	v_permlane16_swap_b32 v77, v79
	global_store_dwordx4 v[142:143], v[76:79], off
	v_pk_mul_f32 v[68:69], v[68:69], v[144:145]
	v_pk_mul_f32 v[70:71], v[70:71], v[144:145]
	v_pk_mul_f32 v[64:65], v[64:65], v[144:145]
	v_pk_mul_f32 v[66:67], v[66:67], v[144:145]
	v_cvt_pk_bf16_f32 v68, v68, v69
	v_cvt_pk_bf16_f32 v69, v70, v71
	v_cvt_pk_bf16_f32 v70, v64, v65
	v_cvt_pk_bf16_f32 v71, v66, v67
	s_nop 1
	v_permlane16_swap_b32 v68, v70
	v_permlane16_swap_b32 v69, v71
	global_store_dwordx4 v[142:143], v[68:71], off offset:256
	v_lshl_add_u64 v[142:143], v[142:143], 0, s[60:61]
	v_pk_mul_f32 v[60:61], v[60:61], v[144:145]
	v_pk_mul_f32 v[62:63], v[62:63], v[144:145]
	v_pk_mul_f32 v[56:57], v[56:57], v[144:145]
	v_pk_mul_f32 v[58:59], v[58:59], v[144:145]
	v_cvt_pk_bf16_f32 v60, v60, v61
	v_cvt_pk_bf16_f32 v61, v62, v63
	v_cvt_pk_bf16_f32 v62, v56, v57
	v_cvt_pk_bf16_f32 v63, v58, v59
	s_nop 1
	v_permlane16_swap_b32 v60, v62
	v_permlane16_swap_b32 v61, v63
	global_store_dwordx4 v[142:143], v[60:63], off
	v_pk_mul_f32 v[52:53], v[52:53], v[144:145]
	v_pk_mul_f32 v[54:55], v[54:55], v[144:145]
	v_pk_mul_f32 v[48:49], v[48:49], v[144:145]
	v_pk_mul_f32 v[50:51], v[50:51], v[144:145]
	v_cvt_pk_bf16_f32 v52, v52, v53
	v_cvt_pk_bf16_f32 v53, v54, v55
	v_cvt_pk_bf16_f32 v54, v48, v49
	v_cvt_pk_bf16_f32 v55, v50, v51
	s_nop 1
	v_permlane16_swap_b32 v52, v54
	v_permlane16_swap_b32 v53, v55
	global_store_dwordx4 v[142:143], v[52:55], off offset:256
	v_lshl_add_u64 v[142:143], v[142:143], 0, s[58:59]
	v_pk_mul_f32 v[44:45], v[44:45], v[144:145]
	v_pk_mul_f32 v[46:47], v[46:47], v[144:145]
	v_pk_mul_f32 v[40:41], v[40:41], v[144:145]
	v_pk_mul_f32 v[42:43], v[42:43], v[144:145]
	v_cvt_pk_bf16_f32 v44, v44, v45
	v_cvt_pk_bf16_f32 v45, v46, v47
	v_cvt_pk_bf16_f32 v46, v40, v41
	v_cvt_pk_bf16_f32 v47, v42, v43
	s_nop 1
	v_permlane16_swap_b32 v44, v46
	v_permlane16_swap_b32 v45, v47
	global_store_dwordx4 v[142:143], v[44:47], off
	v_pk_mul_f32 v[36:37], v[36:37], v[144:145]
	v_pk_mul_f32 v[38:39], v[38:39], v[144:145]
	v_pk_mul_f32 v[32:33], v[32:33], v[144:145]
	v_pk_mul_f32 v[34:35], v[34:35], v[144:145]
	v_cvt_pk_bf16_f32 v36, v36, v37
	v_cvt_pk_bf16_f32 v37, v38, v39
	v_cvt_pk_bf16_f32 v38, v32, v33
	v_cvt_pk_bf16_f32 v39, v34, v35
	s_nop 1
	v_permlane16_swap_b32 v36, v38
	v_permlane16_swap_b32 v37, v39
	global_store_dwordx4 v[142:143], v[36:39], off offset:256
	v_lshl_add_u64 v[142:143], v[142:143], 0, s[58:59]
	v_pk_mul_f32 v[28:29], v[28:29], v[144:145]
	v_pk_mul_f32 v[30:31], v[30:31], v[144:145]
	v_pk_mul_f32 v[24:25], v[24:25], v[144:145]
	v_pk_mul_f32 v[26:27], v[26:27], v[144:145]
	v_cvt_pk_bf16_f32 v28, v28, v29
	v_cvt_pk_bf16_f32 v29, v30, v31
	v_cvt_pk_bf16_f32 v30, v24, v25
	v_cvt_pk_bf16_f32 v31, v26, v27
	s_nop 1
	v_permlane16_swap_b32 v28, v30
	v_permlane16_swap_b32 v29, v31
	global_store_dwordx4 v[142:143], v[28:31], off
	v_pk_mul_f32 v[20:21], v[20:21], v[144:145]
	v_pk_mul_f32 v[22:23], v[22:23], v[144:145]
	v_pk_mul_f32 v[16:17], v[16:17], v[144:145]
	v_pk_mul_f32 v[18:19], v[18:19], v[144:145]
	v_cvt_pk_bf16_f32 v20, v20, v21
	v_cvt_pk_bf16_f32 v21, v22, v23
	v_cvt_pk_bf16_f32 v22, v16, v17
	v_cvt_pk_bf16_f32 v23, v18, v19
	s_nop 1
	v_permlane16_swap_b32 v20, v22
	v_permlane16_swap_b32 v21, v23
	global_store_dwordx4 v[142:143], v[20:23], off offset:256
	v_lshl_add_u64 v[142:143], v[142:143], 0, s[58:59]
	v_pk_mul_f32 v[12:13], v[12:13], v[144:145]
	v_pk_mul_f32 v[14:15], v[14:15], v[144:145]
	v_pk_mul_f32 v[8:9], v[8:9], v[144:145]
	v_pk_mul_f32 v[10:11], v[10:11], v[144:145]
	v_cvt_pk_bf16_f32 v12, v12, v13
	v_cvt_pk_bf16_f32 v13, v14, v15
	v_cvt_pk_bf16_f32 v14, v8, v9
	v_cvt_pk_bf16_f32 v15, v10, v11
	s_nop 1
	v_permlane16_swap_b32 v12, v14
	v_permlane16_swap_b32 v13, v15
	global_store_dwordx4 v[142:143], v[12:15], off
	v_pk_mul_f32 v[4:5], v[4:5], v[144:145]
	v_pk_mul_f32 v[6:7], v[6:7], v[144:145]
	v_pk_mul_f32 v[0:1], v[0:1], v[144:145]
	v_pk_mul_f32 v[2:3], v[2:3], v[144:145]
	v_cvt_pk_bf16_f32 v4, v4, v5
	v_cvt_pk_bf16_f32 v5, v6, v7
	v_cvt_pk_bf16_f32 v6, v0, v1
	v_cvt_pk_bf16_f32 v7, v2, v3
	s_nop 1
	v_permlane16_swap_b32 v4, v6
	v_permlane16_swap_b32 v5, v7
	global_store_dwordx4 v[142:143], v[4:7], off offset:256
	s_movk_i32 s42, 0x210
	s_movk_i32 s43, 0x90
	s_branch .LBB0_562
.Lqk_k:
	s_add_u32 s40, s78, 0xa800000
	s_addc_u32 s41, s79, 0
	v_lshl_add_u64 v[142:143], s[40:41], 0, v[142:143]
	s_cmp_lt_u32 s2, 32
	s_cbranch_scc0 .Lqk_ks
	s_lshl_b32 s40, s2, 4
	s_lshl_b32 s41, s34, 2
	s_add_u32 s40, s40, s41
	s_lshr_b32 s41, s3, 1
	s_add_u32 s40, s40, s41
	s_lshl_b32 s40, s40, 8
	s_add_u32 s40, s40, s33
	v_add_u32_e32 v146, s40, v140
	v_lshlrev_b32_e32 v146, 8, v146
	s_and_b32 s41, s3, 1
	s_lshl_b32 s41, s41, 7
	v_lshl_add_u32 v146, v141, 4, v146
	v_add_u32_e32 v146, s41, v146
	v_mov_b32_e32 v147, 0
	s_add_u32 s40, s76, 0x3000000
	s_addc_u32 s41, s77, 0
	s_mov_b64 s[42:43], 0x20000
	v_lshl_add_u64 v[146:147], s[40:41], 0, v[146:147]
	v_lshl_add_u64 v[148:149], v[146:147], 0, s[42:43]
	s_mov_b64 s[40:41], 0x1000
	s_mov_b64 s[42:43], 0x5000
	global_store_dwordx4 v[146:147], v[124:127], off nt
	global_store_dwordx4 v[146:147], v[120:123], off offset:64 nt
	global_store_dwordx4 v[148:149], v[116:119], off nt
	global_store_dwordx4 v[148:149], v[112:115], off offset:64 nt
	v_cvt_pk_bf16_f32 v124, v124, v125
	v_cvt_pk_bf16_f32 v125, v126, v127
	v_cvt_pk_bf16_f32 v126, v120, v121
	v_cvt_pk_bf16_f32 v127, v122, v123
	s_nop 1
	v_permlane16_swap_b32 v124, v126
	v_permlane16_swap_b32 v125, v127
	global_store_dwordx4 v[142:143], v[124:127], off
	v_cvt_pk_bf16_f32 v116, v116, v117
	v_cvt_pk_bf16_f32 v117, v118, v119
	v_cvt_pk_bf16_f32 v118, v112, v113
	v_cvt_pk_bf16_f32 v119, v114, v115
	s_nop 1
	v_permlane16_swap_b32 v116, v118
	v_permlane16_swap_b32 v117, v119
	global_store_dwordx4 v[142:143], v[116:119], off offset:256
	v_lshl_add_u64 v[142:143], v[142:143], 0, s[58:59]
	v_lshl_add_u64 v[146:147], v[146:147], 0, s[40:41]
	v_lshl_add_u64 v[148:149], v[148:149], 0, s[40:41]
	global_store_dwordx4 v[146:147], v[108:111], off nt
	global_store_dwordx4 v[146:147], v[104:107], off offset:64 nt
	global_store_dwordx4 v[148:149], v[100:103], off nt
	global_store_dwordx4 v[148:149], v[96:99], off offset:64 nt
	v_cvt_pk_bf16_f32 v108, v108, v109
	v_cvt_pk_bf16_f32 v109, v110, v111
	v_cvt_pk_bf16_f32 v110, v104, v105
	v_cvt_pk_bf16_f32 v111, v106, v107
	s_nop 1
	v_permlane16_swap_b32 v108, v110
	v_permlane16_swap_b32 v109, v111
	global_store_dwordx4 v[142:143], v[108:111], off
	v_cvt_pk_bf16_f32 v100, v100, v101
	v_cvt_pk_bf16_f32 v101, v102, v103
	v_cvt_pk_bf16_f32 v102, v96, v97
	v_cvt_pk_bf16_f32 v103, v98, v99
	s_nop 1
	v_permlane16_swap_b32 v100, v102
	v_permlane16_swap_b32 v101, v103
	global_store_dwordx4 v[142:143], v[100:103], off offset:256
	v_lshl_add_u64 v[142:143], v[142:143], 0, s[58:59]
	v_lshl_add_u64 v[146:147], v[146:147], 0, s[40:41]
	v_lshl_add_u64 v[148:149], v[148:149], 0, s[40:41]
	global_store_dwordx4 v[146:147], v[92:95], off nt
	global_store_dwordx4 v[146:147], v[88:91], off offset:64 nt
	global_store_dwordx4 v[148:149], v[84:87], off nt
	global_store_dwordx4 v[148:149], v[80:83], off offset:64 nt
	v_cvt_pk_bf16_f32 v92, v92, v93
	v_cvt_pk_bf16_f32 v93, v94, v95
	v_cvt_pk_bf16_f32 v94, v88, v89
	v_cvt_pk_bf16_f32 v95, v90, v91
	s_nop 1
	v_permlane16_swap_b32 v92, v94
	v_permlane16_swap_b32 v93, v95
	global_store_dwordx4 v[142:143], v[92:95], off
	v_cvt_pk_bf16_f32 v84, v84, v85
	v_cvt_pk_bf16_f32 v85, v86, v87
	v_cvt_pk_bf16_f32 v86, v80, v81
	v_cvt_pk_bf16_f32 v87, v82, v83
	s_nop 1
	v_permlane16_swap_b32 v84, v86
	v_permlane16_swap_b32 v85, v87
	global_store_dwordx4 v[142:143], v[84:87], off offset:256
	v_lshl_add_u64 v[142:143], v[142:143], 0, s[58:59]
	v_lshl_add_u64 v[146:147], v[146:147], 0, s[40:41]
	v_lshl_add_u64 v[148:149], v[148:149], 0, s[40:41]
	global_store_dwordx4 v[146:147], v[76:79], off nt
	global_store_dwordx4 v[146:147], v[72:75], off offset:64 nt
	global_store_dwordx4 v[148:149], v[68:71], off nt
	global_store_dwordx4 v[148:149], v[64:67], off offset:64 nt
	v_cvt_pk_bf16_f32 v76, v76, v77
	v_cvt_pk_bf16_f32 v77, v78, v79
	v_cvt_pk_bf16_f32 v78, v72, v73
	v_cvt_pk_bf16_f32 v79, v74, v75
	s_nop 1
	v_permlane16_swap_b32 v76, v78
	v_permlane16_swap_b32 v77, v79
	global_store_dwordx4 v[142:143], v[76:79], off
	v_cvt_pk_bf16_f32 v68, v68, v69
	v_cvt_pk_bf16_f32 v69, v70, v71
	v_cvt_pk_bf16_f32 v70, v64, v65
	v_cvt_pk_bf16_f32 v71, v66, v67
	s_nop 1
	v_permlane16_swap_b32 v68, v70
	v_permlane16_swap_b32 v69, v71
	global_store_dwordx4 v[142:143], v[68:71], off offset:256
	v_lshl_add_u64 v[142:143], v[142:143], 0, s[60:61]
	v_lshl_add_u64 v[146:147], v[146:147], 0, s[42:43]
	v_lshl_add_u64 v[148:149], v[148:149], 0, s[42:43]
	global_store_dwordx4 v[146:147], v[60:63], off nt
	global_store_dwordx4 v[146:147], v[56:59], off offset:64 nt
	global_store_dwordx4 v[148:149], v[52:55], off nt
	global_store_dwordx4 v[148:149], v[48:51], off offset:64 nt
	v_cvt_pk_bf16_f32 v60, v60, v61
	v_cvt_pk_bf16_f32 v61, v62, v63
	v_cvt_pk_bf16_f32 v62, v56, v57
	v_cvt_pk_bf16_f32 v63, v58, v59
	s_nop 1
	v_permlane16_swap_b32 v60, v62
	v_permlane16_swap_b32 v61, v63
	global_store_dwordx4 v[142:143], v[60:63], off
	v_cvt_pk_bf16_f32 v52, v52, v53
	v_cvt_pk_bf16_f32 v53, v54, v55
	v_cvt_pk_bf16_f32 v54, v48, v49
	v_cvt_pk_bf16_f32 v55, v50, v51
	s_nop 1
	v_permlane16_swap_b32 v52, v54
	v_permlane16_swap_b32 v53, v55
	global_store_dwordx4 v[142:143], v[52:55], off offset:256
	v_lshl_add_u64 v[142:143], v[142:143], 0, s[58:59]
	v_lshl_add_u64 v[146:147], v[146:147], 0, s[40:41]
	v_lshl_add_u64 v[148:149], v[148:149], 0, s[40:41]
	global_store_dwordx4 v[146:147], v[44:47], off nt
	global_store_dwordx4 v[146:147], v[40:43], off offset:64 nt
	global_store_dwordx4 v[148:149], v[36:39], off nt
	global_store_dwordx4 v[148:149], v[32:35], off offset:64 nt
	v_cvt_pk_bf16_f32 v44, v44, v45
	v_cvt_pk_bf16_f32 v45, v46, v47
	v_cvt_pk_bf16_f32 v46, v40, v41
	v_cvt_pk_bf16_f32 v47, v42, v43
	s_nop 1
	v_permlane16_swap_b32 v44, v46
	v_permlane16_swap_b32 v45, v47
	global_store_dwordx4 v[142:143], v[44:47], off
	v_cvt_pk_bf16_f32 v36, v36, v37
	v_cvt_pk_bf16_f32 v37, v38, v39
	v_cvt_pk_bf16_f32 v38, v32, v33
	v_cvt_pk_bf16_f32 v39, v34, v35
	s_nop 1
	v_permlane16_swap_b32 v36, v38
	v_permlane16_swap_b32 v37, v39
	global_store_dwordx4 v[142:143], v[36:39], off offset:256
	v_lshl_add_u64 v[142:143], v[142:143], 0, s[58:59]
	v_lshl_add_u64 v[146:147], v[146:147], 0, s[40:41]
	v_lshl_add_u64 v[148:149], v[148:149], 0, s[40:41]
	global_store_dwordx4 v[146:147], v[28:31], off nt
	global_store_dwordx4 v[146:147], v[24:27], off offset:64 nt
	global_store_dwordx4 v[148:149], v[20:23], off nt
	global_store_dwordx4 v[148:149], v[16:19], off offset:64 nt
	v_cvt_pk_bf16_f32 v28, v28, v29
	v_cvt_pk_bf16_f32 v29, v30, v31
	v_cvt_pk_bf16_f32 v30, v24, v25
	v_cvt_pk_bf16_f32 v31, v26, v27
	s_nop 1
	v_permlane16_swap_b32 v28, v30
	v_permlane16_swap_b32 v29, v31
	global_store_dwordx4 v[142:143], v[28:31], off
	v_cvt_pk_bf16_f32 v20, v20, v21
	v_cvt_pk_bf16_f32 v21, v22, v23
	v_cvt_pk_bf16_f32 v22, v16, v17
	v_cvt_pk_bf16_f32 v23, v18, v19
	s_nop 1
	v_permlane16_swap_b32 v20, v22
	v_permlane16_swap_b32 v21, v23
	global_store_dwordx4 v[142:143], v[20:23], off offset:256
	v_lshl_add_u64 v[142:143], v[142:143], 0, s[58:59]
	v_lshl_add_u64 v[146:147], v[146:147], 0, s[40:41]
	v_lshl_add_u64 v[148:149], v[148:149], 0, s[40:41]
	global_store_dwordx4 v[146:147], v[12:15], off nt
	global_store_dwordx4 v[146:147], v[8:11], off offset:64 nt
	global_store_dwordx4 v[148:149], v[4:7], off nt
	global_store_dwordx4 v[148:149], v[0:3], off offset:64 nt
	v_cvt_pk_bf16_f32 v12, v12, v13
	v_cvt_pk_bf16_f32 v13, v14, v15
	v_cvt_pk_bf16_f32 v14, v8, v9
	v_cvt_pk_bf16_f32 v15, v10, v11
	s_nop 1
	v_permlane16_swap_b32 v12, v14
	v_permlane16_swap_b32 v13, v15
	global_store_dwordx4 v[142:143], v[12:15], off
	v_cvt_pk_bf16_f32 v4, v4, v5
	v_cvt_pk_bf16_f32 v5, v6, v7
	v_cvt_pk_bf16_f32 v6, v0, v1
	v_cvt_pk_bf16_f32 v7, v2, v3
	s_nop 1
	v_permlane16_swap_b32 v4, v6
	v_permlane16_swap_b32 v5, v7
	global_store_dwordx4 v[142:143], v[4:7], off offset:256
	s_movk_i32 s42, 0x210
	s_movk_i32 s43, 0x90
	s_branch .LBB0_562
.Lqk_ks:
	v_cvt_pk_bf16_f32 v124, v124, v125
	v_cvt_pk_bf16_f32 v125, v126, v127
	v_cvt_pk_bf16_f32 v126, v120, v121
	v_cvt_pk_bf16_f32 v127, v122, v123
	s_nop 1
	v_permlane16_swap_b32 v124, v126
	v_permlane16_swap_b32 v125, v127
	global_store_dwordx4 v[142:143], v[124:127], off
	v_cvt_pk_bf16_f32 v116, v116, v117
	v_cvt_pk_bf16_f32 v117, v118, v119
	v_cvt_pk_bf16_f32 v118, v112, v113
	v_cvt_pk_bf16_f32 v119, v114, v115
	s_nop 1
	v_permlane16_swap_b32 v116, v118
	v_permlane16_swap_b32 v117, v119
	global_store_dwordx4 v[142:143], v[116:119], off offset:256
	v_lshl_add_u64 v[142:143], v[142:143], 0, s[58:59]
	v_cvt_pk_bf16_f32 v108, v108, v109
	v_cvt_pk_bf16_f32 v109, v110, v111
	v_cvt_pk_bf16_f32 v110, v104, v105
	v_cvt_pk_bf16_f32 v111, v106, v107
	s_nop 1
	v_permlane16_swap_b32 v108, v110
	v_permlane16_swap_b32 v109, v111
	global_store_dwordx4 v[142:143], v[108:111], off
	v_cvt_pk_bf16_f32 v100, v100, v101
	v_cvt_pk_bf16_f32 v101, v102, v103
	v_cvt_pk_bf16_f32 v102, v96, v97
	v_cvt_pk_bf16_f32 v103, v98, v99
	s_nop 1
	v_permlane16_swap_b32 v100, v102
	v_permlane16_swap_b32 v101, v103
	global_store_dwordx4 v[142:143], v[100:103], off offset:256
	v_lshl_add_u64 v[142:143], v[142:143], 0, s[58:59]
	v_cvt_pk_bf16_f32 v92, v92, v93
	v_cvt_pk_bf16_f32 v93, v94, v95
	v_cvt_pk_bf16_f32 v94, v88, v89
	v_cvt_pk_bf16_f32 v95, v90, v91
	s_nop 1
	v_permlane16_swap_b32 v92, v94
	v_permlane16_swap_b32 v93, v95
	global_store_dwordx4 v[142:143], v[92:95], off
	v_cvt_pk_bf16_f32 v84, v84, v85
	v_cvt_pk_bf16_f32 v85, v86, v87
	v_cvt_pk_bf16_f32 v86, v80, v81
	v_cvt_pk_bf16_f32 v87, v82, v83
	s_nop 1
	v_permlane16_swap_b32 v84, v86
	v_permlane16_swap_b32 v85, v87
	global_store_dwordx4 v[142:143], v[84:87], off offset:256
	v_lshl_add_u64 v[142:143], v[142:143], 0, s[58:59]
	v_cvt_pk_bf16_f32 v76, v76, v77
	v_cvt_pk_bf16_f32 v77, v78, v79
	v_cvt_pk_bf16_f32 v78, v72, v73
	v_cvt_pk_bf16_f32 v79, v74, v75
	s_nop 1
	v_permlane16_swap_b32 v76, v78
	v_permlane16_swap_b32 v77, v79
	global_store_dwordx4 v[142:143], v[76:79], off
	v_cvt_pk_bf16_f32 v68, v68, v69
	v_cvt_pk_bf16_f32 v69, v70, v71
	v_cvt_pk_bf16_f32 v70, v64, v65
	v_cvt_pk_bf16_f32 v71, v66, v67
	s_nop 1
	v_permlane16_swap_b32 v68, v70
	v_permlane16_swap_b32 v69, v71
	global_store_dwordx4 v[142:143], v[68:71], off offset:256
	v_lshl_add_u64 v[142:143], v[142:143], 0, s[60:61]
	v_cvt_pk_bf16_f32 v60, v60, v61
	v_cvt_pk_bf16_f32 v61, v62, v63
	v_cvt_pk_bf16_f32 v62, v56, v57
	v_cvt_pk_bf16_f32 v63, v58, v59
	s_nop 1
	v_permlane16_swap_b32 v60, v62
	v_permlane16_swap_b32 v61, v63
	global_store_dwordx4 v[142:143], v[60:63], off
	v_cvt_pk_bf16_f32 v52, v52, v53
	v_cvt_pk_bf16_f32 v53, v54, v55
	v_cvt_pk_bf16_f32 v54, v48, v49
	v_cvt_pk_bf16_f32 v55, v50, v51
	s_nop 1
	v_permlane16_swap_b32 v52, v54
	v_permlane16_swap_b32 v53, v55
	global_store_dwordx4 v[142:143], v[52:55], off offset:256
	v_lshl_add_u64 v[142:143], v[142:143], 0, s[58:59]
	v_cvt_pk_bf16_f32 v44, v44, v45
	v_cvt_pk_bf16_f32 v45, v46, v47
	v_cvt_pk_bf16_f32 v46, v40, v41
	v_cvt_pk_bf16_f32 v47, v42, v43
	s_nop 1
	v_permlane16_swap_b32 v44, v46
	v_permlane16_swap_b32 v45, v47
	global_store_dwordx4 v[142:143], v[44:47], off
	v_cvt_pk_bf16_f32 v36, v36, v37
	v_cvt_pk_bf16_f32 v37, v38, v39
	v_cvt_pk_bf16_f32 v38, v32, v33
	v_cvt_pk_bf16_f32 v39, v34, v35
	s_nop 1
	v_permlane16_swap_b32 v36, v38
	v_permlane16_swap_b32 v37, v39
	global_store_dwordx4 v[142:143], v[36:39], off offset:256
	v_lshl_add_u64 v[142:143], v[142:143], 0, s[58:59]
	v_cvt_pk_bf16_f32 v28, v28, v29
	v_cvt_pk_bf16_f32 v29, v30, v31
	v_cvt_pk_bf16_f32 v30, v24, v25
	v_cvt_pk_bf16_f32 v31, v26, v27
	s_nop 1
	v_permlane16_swap_b32 v28, v30
	v_permlane16_swap_b32 v29, v31
	global_store_dwordx4 v[142:143], v[28:31], off
	v_cvt_pk_bf16_f32 v20, v20, v21
	v_cvt_pk_bf16_f32 v21, v22, v23
	v_cvt_pk_bf16_f32 v22, v16, v17
	v_cvt_pk_bf16_f32 v23, v18, v19
	s_nop 1
	v_permlane16_swap_b32 v20, v22
	v_permlane16_swap_b32 v21, v23
	global_store_dwordx4 v[142:143], v[20:23], off offset:256
	v_lshl_add_u64 v[142:143], v[142:143], 0, s[58:59]
	v_cvt_pk_bf16_f32 v12, v12, v13
	v_cvt_pk_bf16_f32 v13, v14, v15
	v_cvt_pk_bf16_f32 v14, v8, v9
	v_cvt_pk_bf16_f32 v15, v10, v11
	s_nop 1
	v_permlane16_swap_b32 v12, v14
	v_permlane16_swap_b32 v13, v15
	global_store_dwordx4 v[142:143], v[12:15], off
	v_cvt_pk_bf16_f32 v4, v4, v5
	v_cvt_pk_bf16_f32 v5, v6, v7
	v_cvt_pk_bf16_f32 v6, v0, v1
	v_cvt_pk_bf16_f32 v7, v2, v3
	s_nop 1
	v_permlane16_swap_b32 v4, v6
	v_permlane16_swap_b32 v5, v7
	global_store_dwordx4 v[142:143], v[4:7], off offset:256
	s_movk_i32 s42, 0x210
	s_movk_i32 s43, 0x90
	s_branch .LBB0_562
